# P1 epilogue: tiles with scale 1.0 (12 of 17) branch to a copy without the 64 packed multiplies
# speedup vs baseline: 1.0103x; 1.0060x over previous
; __device__ __forceinline__ size_t tm_block(int pm, int ct, int nct) { return ((size_t)pm * nct + ct) * 32768; }
; __device__ __forceinline__ u32x4 pack8(const f32x4& v0, const f32x4& v1) { u32x4 w; w.x = cvt_pk_bf16(v0[0], v0[1]); w.y = cvt_pk_bf16(v0[2], v0[3]); w.z = cvt_pk_bf16(v1[0], v1[1]); w.w = cvt_pk_bf16(v1[2], v1[3]); return w; }
;     __device__ __forceinline__ void operator()(const f32x4 (&acc)[2][2][4][2], const Unit& u, int wr, int wc, int fr, int fq) const {
;         const PieceOut po(scr, O, tm_block(u.pm, u.pn * 4 + wc, nct), wr, wc, fr, fq);
;         const float qs = (u.pn < 2 || u.pn == 3 || u.pn == 4) ? 0.125f * 1.4426950408889634f : 1.0f;
; #pragma unroll
;         for (int ai = 0; ai < 2; ++ai)
; #pragma unroll
;             for (int m = 0; m < 4; ++m) { po.put(0, pack8(acc[ai][0][m][0] * qs, acc[ai][0][m][1] * qs)); po.put(1, pack8(acc[ai][1][m][0] * qs, acc[ai][1][m][1] * qs)); po.flush<true>(ai, m); }
;     }
.LBB0_153:
	s_lshl_b32 s15, s70, 2
	s_or_b32 s15, s15, s53
	s_mul_hi_i32 s17, s22, 0x44
	s_mulk_i32 s22, 0x44
	s_ashr_i32 s25, s15, 31
	s_add_u32 s24, s22, s15
	s_addc_u32 s25, s17, s25
	s_lshl_b64 s[24:25], s[24:25], 15
	s_cmp_lt_i32 s70, 2
	s_cselect_b64 s[26:27], -1, 0
	s_add_i32 s15, s70, -3
	s_cmp_lt_u32 s15, 2
	s_cselect_b64 s[28:29], -1, 0
	s_or_b64 vcc, s[26:27], s[28:29]
	s_cbranch_vccz .Lp1_epi_plain
	v_cndmask_b32_e32 v148, 1.0, v155, vcc
	v_pk_mul_f32 v[128:129], v[148:149], v[128:129] op_sel_hi:[0,1]
	v_pk_mul_f32 v[126:127], v[148:149], v[126:127] op_sel_hi:[0,1]
	v_pk_mul_f32 v[156:157], v[148:149], v[124:125] op_sel_hi:[0,1]
	v_pk_mul_f32 v[124:125], v[148:149], v[122:123] op_sel_hi:[0,1]
	v_cvt_pk_bf16_f32 v122, v126, v127
	v_cvt_pk_bf16_f32 v123, v128, v129
	v_cvt_pk_bf16_f32 v124, v124, v125
	v_cvt_pk_bf16_f32 v125, v156, v157
	ds_write_b128 v153, v[122:125]
	v_pk_mul_f32 v[122:123], v[148:149], v[112:113] op_sel_hi:[0,1]
	v_pk_mul_f32 v[112:113], v[148:149], v[110:111] op_sel_hi:[0,1]
	v_pk_mul_f32 v[120:121], v[148:149], v[120:121] op_sel_hi:[0,1]
	v_pk_mul_f32 v[118:119], v[148:149], v[118:119] op_sel_hi:[0,1]
	v_cvt_pk_bf16_f32 v110, v118, v119
	v_cvt_pk_bf16_f32 v111, v120, v121
	v_cvt_pk_bf16_f32 v112, v112, v113
	v_cvt_pk_bf16_f32 v113, v122, v123
	ds_write_b128 v153, v[110:113] offset:64
	ds_read_b128 v[110:113], v154
	ds_read_b128 v[118:121], v154 offset:1152
	v_lshl_add_u64 v[122:123], v[138:139], 0, s[24:25]
	s_waitcnt lgkmcnt(0)
	global_store_dwordx4 v[122:123], v[110:113], off nt
	global_store_dwordx4 v[122:123], v[118:121], off offset:1024 nt
	s_nop 0
	v_pk_mul_f32 v[110:111], v[148:149], v[116:117] op_sel_hi:[0,1]
	v_pk_mul_f32 v[112:113], v[148:149], v[114:115] op_sel_hi:[0,1]
	v_pk_mul_f32 v[114:115], v[148:149], v[108:109] op_sel_hi:[0,1]
	v_pk_mul_f32 v[108:109], v[148:149], v[106:107] op_sel_hi:[0,1]
	v_cvt_pk_bf16_f32 v106, v112, v113
	v_cvt_pk_bf16_f32 v107, v110, v111
	v_cvt_pk_bf16_f32 v108, v108, v109
	v_cvt_pk_bf16_f32 v109, v114, v115
	ds_write_b128 v153, v[106:109]
	v_pk_mul_f32 v[106:107], v[148:149], v[96:97] op_sel_hi:[0,1]
	v_pk_mul_f32 v[96:97], v[148:149], v[94:95] op_sel_hi:[0,1]
	v_pk_mul_f32 v[104:105], v[148:149], v[104:105] op_sel_hi:[0,1]
	v_pk_mul_f32 v[102:103], v[148:149], v[102:103] op_sel_hi:[0,1]
	v_cvt_pk_bf16_f32 v94, v102, v103
	v_cvt_pk_bf16_f32 v95, v104, v105
	v_cvt_pk_bf16_f32 v96, v96, v97
	v_cvt_pk_bf16_f32 v97, v106, v107
	ds_write_b128 v153, v[94:97] offset:64
	ds_read_b128 v[94:97], v154
	ds_read_b128 v[102:105], v154 offset:1152
	s_waitcnt lgkmcnt(0)
	global_store_dwordx4 v[122:123], v[94:97], off offset:2048 nt
	global_store_dwordx4 v[122:123], v[102:105], off offset:3072 nt
	s_nop 0
	v_pk_mul_f32 v[94:95], v[148:149], v[100:101] op_sel_hi:[0,1]
	v_pk_mul_f32 v[96:97], v[148:149], v[98:99] op_sel_hi:[0,1]
	v_pk_mul_f32 v[98:99], v[148:149], v[92:93] op_sel_hi:[0,1]
	v_pk_mul_f32 v[92:93], v[148:149], v[90:91] op_sel_hi:[0,1]
	v_cvt_pk_bf16_f32 v90, v96, v97
	v_cvt_pk_bf16_f32 v91, v94, v95
	v_cvt_pk_bf16_f32 v92, v92, v93
	v_cvt_pk_bf16_f32 v93, v98, v99
	ds_write_b128 v153, v[90:93]
	v_pk_mul_f32 v[90:91], v[148:149], v[84:85] op_sel_hi:[0,1]
	v_pk_mul_f32 v[84:85], v[148:149], v[82:83] op_sel_hi:[0,1]
	v_pk_mul_f32 v[88:89], v[148:149], v[88:89] op_sel_hi:[0,1]
	v_pk_mul_f32 v[86:87], v[148:149], v[86:87] op_sel_hi:[0,1]
	v_cvt_pk_bf16_f32 v82, v86, v87
	v_cvt_pk_bf16_f32 v83, v88, v89
	v_cvt_pk_bf16_f32 v84, v84, v85
	v_cvt_pk_bf16_f32 v85, v90, v91
	ds_write_b128 v153, v[82:85] offset:64
	ds_read_b128 v[82:85], v154
	ds_read_b128 v[86:89], v154 offset:1152
	v_add_co_u32_e32 v90, vcc, s58, v122
	v_pk_mul_f32 v[80:81], v[148:149], v[80:81] op_sel_hi:[0,1]
	s_nop 0
	v_addc_co_u32_e32 v91, vcc, 0, v123, vcc
	s_waitcnt lgkmcnt(0)
	global_store_dwordx4 v[90:91], v[82:85], off nt
	global_store_dwordx4 v[90:91], v[86:89], off offset:1024 nt
	v_pk_mul_f32 v[78:79], v[148:149], v[78:79] op_sel_hi:[0,1]
	v_pk_mul_f32 v[82:83], v[148:149], v[76:77] op_sel_hi:[0,1]
	v_pk_mul_f32 v[76:77], v[148:149], v[74:75] op_sel_hi:[0,1]
	v_cvt_pk_bf16_f32 v74, v78, v79
	v_cvt_pk_bf16_f32 v75, v80, v81
	v_cvt_pk_bf16_f32 v76, v76, v77
	v_cvt_pk_bf16_f32 v77, v82, v83
	ds_write_b128 v153, v[74:77]
	v_pk_mul_f32 v[74:75], v[148:149], v[68:69] op_sel_hi:[0,1]
	v_pk_mul_f32 v[68:69], v[148:149], v[66:67] op_sel_hi:[0,1]
	v_pk_mul_f32 v[72:73], v[148:149], v[72:73] op_sel_hi:[0,1]
	v_pk_mul_f32 v[70:71], v[148:149], v[70:71] op_sel_hi:[0,1]
	v_cvt_pk_bf16_f32 v66, v70, v71
	v_cvt_pk_bf16_f32 v67, v72, v73
	v_cvt_pk_bf16_f32 v68, v68, v69
	v_cvt_pk_bf16_f32 v69, v74, v75
	ds_write_b128 v153, v[66:69] offset:64
	ds_read_b128 v[66:69], v154
	ds_read_b128 v[70:73], v154 offset:1152
	s_waitcnt lgkmcnt(0)
	global_store_dwordx4 v[90:91], v[66:69], off offset:2048 nt
	global_store_dwordx4 v[90:91], v[70:73], off offset:3072 nt
	v_pk_mul_f32 v[64:65], v[148:149], v[64:65] op_sel_hi:[0,1]
	v_pk_mul_f32 v[62:63], v[148:149], v[62:63] op_sel_hi:[0,1]
	v_pk_mul_f32 v[66:67], v[148:149], v[60:61] op_sel_hi:[0,1]
	v_pk_mul_f32 v[60:61], v[148:149], v[58:59] op_sel_hi:[0,1]
	v_cvt_pk_bf16_f32 v58, v62, v63
	v_cvt_pk_bf16_f32 v59, v64, v65
	v_cvt_pk_bf16_f32 v60, v60, v61
	v_cvt_pk_bf16_f32 v61, v66, v67
	ds_write_b128 v153, v[58:61]
	v_pk_mul_f32 v[58:59], v[148:149], v[52:53] op_sel_hi:[0,1]
	v_pk_mul_f32 v[52:53], v[148:149], v[50:51] op_sel_hi:[0,1]
	v_pk_mul_f32 v[56:57], v[148:149], v[56:57] op_sel_hi:[0,1]
	v_pk_mul_f32 v[54:55], v[148:149], v[54:55] op_sel_hi:[0,1]
	v_cvt_pk_bf16_f32 v50, v54, v55
	v_cvt_pk_bf16_f32 v51, v56, v57
	v_cvt_pk_bf16_f32 v52, v52, v53
	v_cvt_pk_bf16_f32 v53, v58, v59
	ds_write_b128 v153, v[50:53] offset:64
	ds_read_b128 v[50:53], v154
	ds_read_b128 v[54:57], v154 offset:1152
	v_add_co_u32_e32 v58, vcc, s52, v122
	v_pk_mul_f32 v[48:49], v[148:149], v[48:49] op_sel_hi:[0,1]
	s_nop 0
	v_addc_co_u32_e32 v59, vcc, 0, v123, vcc
	v_add_co_u32_e32 v60, vcc, s59, v122
	v_pk_mul_f32 v[46:47], v[148:149], v[46:47] op_sel_hi:[0,1]
	s_nop 0
	v_addc_co_u32_e32 v61, vcc, 0, v123, vcc
	s_waitcnt lgkmcnt(0)
; __device__ __forceinline__ u32x4 pack8(const f32x4& v0, const f32x4& v1) { u32x4 w; w.x = cvt_pk_bf16(v0[0], v0[1]); w.y = cvt_pk_bf16(v0[2], v0[3]); w.z = cvt_pk_bf16(v1[0], v1[1]); w.w = cvt_pk_bf16(v1[2], v1[3]); return w; }
; #define PG8_BAR __builtin_amdgcn_s_barrier()
;     __device__ __forceinline__ void operator()(const f32x4 (&acc)[2][2][4][2], const Unit& u, int wr, int wc, int fr, int fq) const {
;     ...
;         for (int ai = 0; ai < 2; ++ai)
; #pragma unroll
;             for (int m = 0; m < 4; ++m) { po.put(0, pack8(acc[ai][0][m][0] * qs, acc[ai][0][m][1] * qs)); po.put(1, pack8(acc[ai][1][m][0] * qs, acc[ai][1][m][1] * qs)); po.flush<true>(ai, m); }
; template <class Epi, class Sched, bool ALIGN_EPI = false, bool SP2 = false>
; __device__ __forceinline__ void gemm_phase(PG8_LAS unsigned char* lds, const Gemm g, const Sched& S, const Epi& E) {
;     ...
;         if (!has_next) break;
; #pragma unroll
;         for (int a = 0; a < 2; ++a)
; #pragma unroll
;             for (int b = 0; b < 2; ++b)
; #pragma unroll
;                 for (int m = 0; m < 4; ++m)
; #pragma unroll
;                     for (int n = 0; n < 2; ++n) acc[a][b][m][n] = (f32x4){0.f, 0.f, 0.f, 0.f};
;         cur = nxt; cA = nA; cB = nB; ++ui;
;         if constexpr (ALIGN_EPI) { if (wr == 1) PG8_BAR; }
	global_store_dwordx4 v[60:61], v[50:53], off offset:-4096 nt
	global_store_dwordx4 v[58:59], v[54:57], off offset:1024 nt
	v_pk_mul_f32 v[40:41], v[148:149], v[40:41] op_sel_hi:[0,1]
	v_pk_mul_f32 v[50:51], v[148:149], v[44:45] op_sel_hi:[0,1]
	v_pk_mul_f32 v[44:45], v[148:149], v[42:43] op_sel_hi:[0,1]
	v_cvt_pk_bf16_f32 v42, v46, v47
	v_cvt_pk_bf16_f32 v43, v48, v49
	v_cvt_pk_bf16_f32 v44, v44, v45
	v_cvt_pk_bf16_f32 v45, v50, v51
	ds_write_b128 v153, v[42:45]
	v_pk_mul_f32 v[42:43], v[148:149], v[32:33] op_sel_hi:[0,1]
	v_pk_mul_f32 v[32:33], v[148:149], v[30:31] op_sel_hi:[0,1]
	v_pk_mul_f32 v[38:39], v[148:149], v[38:39] op_sel_hi:[0,1]
	v_cvt_pk_bf16_f32 v30, v38, v39
	v_cvt_pk_bf16_f32 v31, v40, v41
	v_cvt_pk_bf16_f32 v32, v32, v33
	v_cvt_pk_bf16_f32 v33, v42, v43
	ds_write_b128 v153, v[30:33] offset:64
	ds_read_b128 v[30:33], v154
	ds_read_b128 v[38:41], v154 offset:1152
	s_waitcnt lgkmcnt(0)
	global_store_dwordx4 v[58:59], v[30:33], off offset:2048 nt
	global_store_dwordx4 v[58:59], v[38:41], off offset:3072 nt
	s_nop 0
	v_pk_mul_f32 v[30:31], v[148:149], v[36:37] op_sel_hi:[0,1]
	v_pk_mul_f32 v[32:33], v[148:149], v[34:35] op_sel_hi:[0,1]
	v_pk_mul_f32 v[34:35], v[148:149], v[28:29] op_sel_hi:[0,1]
	v_pk_mul_f32 v[28:29], v[148:149], v[26:27] op_sel_hi:[0,1]
	v_cvt_pk_bf16_f32 v26, v32, v33
	v_cvt_pk_bf16_f32 v27, v30, v31
	v_cvt_pk_bf16_f32 v28, v28, v29
	v_cvt_pk_bf16_f32 v29, v34, v35
	ds_write_b128 v153, v[26:29]
	v_pk_mul_f32 v[26:27], v[148:149], v[16:17] op_sel_hi:[0,1]
	v_pk_mul_f32 v[16:17], v[148:149], v[14:15] op_sel_hi:[0,1]
	v_pk_mul_f32 v[24:25], v[148:149], v[24:25] op_sel_hi:[0,1]
	v_pk_mul_f32 v[22:23], v[148:149], v[22:23] op_sel_hi:[0,1]
	v_cvt_pk_bf16_f32 v14, v22, v23
	v_cvt_pk_bf16_f32 v15, v24, v25
	v_cvt_pk_bf16_f32 v16, v16, v17
	v_cvt_pk_bf16_f32 v17, v26, v27
	ds_write_b128 v153, v[14:17] offset:64
	ds_read_b128 v[14:17], v154
	ds_read_b128 v[22:25], v154 offset:1152
	s_waitcnt lgkmcnt(0)
	global_store_dwordx4 v[60:61], v[14:17], off nt
	global_store_dwordx4 v[60:61], v[22:25], off offset:1024 nt
	s_nop 0
	v_pk_mul_f32 v[14:15], v[148:149], v[20:21] op_sel_hi:[0,1]
	v_pk_mul_f32 v[16:17], v[148:149], v[18:19] op_sel_hi:[0,1]
	v_pk_mul_f32 v[18:19], v[148:149], v[12:13] op_sel_hi:[0,1]
	v_pk_mul_f32 v[12:13], v[148:149], v[10:11] op_sel_hi:[0,1]
	v_cvt_pk_bf16_f32 v10, v16, v17
	v_cvt_pk_bf16_f32 v11, v14, v15
	v_cvt_pk_bf16_f32 v12, v12, v13
	v_cvt_pk_bf16_f32 v13, v18, v19
	ds_write_b128 v153, v[10:13]
	v_pk_mul_f32 v[10:11], v[148:149], v[4:5] op_sel_hi:[0,1]
	v_pk_mul_f32 v[4:5], v[148:149], v[2:3] op_sel_hi:[0,1]
	v_pk_mul_f32 v[8:9], v[148:149], v[8:9] op_sel_hi:[0,1]
	v_pk_mul_f32 v[6:7], v[148:149], v[6:7] op_sel_hi:[0,1]
	v_cvt_pk_bf16_f32 v2, v6, v7
	v_cvt_pk_bf16_f32 v3, v8, v9
	v_cvt_pk_bf16_f32 v4, v4, v5
	v_cvt_pk_bf16_f32 v5, v10, v11
	ds_write_b128 v153, v[2:5] offset:64
	ds_read_b128 v[2:5], v154
	ds_read_b128 v[6:9], v154 offset:1152
	s_andn2_b64 vcc, exec, s[4:5]
	s_mov_b64 s[4:5], -1
	s_waitcnt lgkmcnt(0)
	global_store_dwordx4 v[60:61], v[2:5], off offset:2048 nt
	global_store_dwordx4 v[60:61], v[6:9], off offset:3072 nt
.Lp1_epi_join:
	s_cbranch_vccnz .LBB0_146
	s_andn2_b64 vcc, exec, s[10:11]
	s_cbranch_vccnz .LBB0_145
	s_barrier
	s_branch .LBB0_145
; __device__ __forceinline__ size_t tm_block(int pm, int ct, int nct) { return ((size_t)pm * nct + ct) * 32768; }
; __device__ __forceinline__ u32x4 pack8(const f32x4& v0, const f32x4& v1) { u32x4 w; w.x = cvt_pk_bf16(v0[0], v0[1]); w.y = cvt_pk_bf16(v0[2], v0[3]); w.z = cvt_pk_bf16(v1[0], v1[1]); w.w = cvt_pk_bf16(v1[2], v1[3]); return w; }
;     __device__ __forceinline__ void operator()(const f32x4 (&acc)[2][2][4][2], const Unit& u, int wr, int wc, int fr, int fq) const {
;         const PieceOut po(scr, O, tm_block(u.pm, u.pn * 4 + wc, nct), wr, wc, fr, fq);
;         const float qs = (u.pn < 2 || u.pn == 3 || u.pn == 4) ? 0.125f * 1.4426950408889634f : 1.0f;
; #pragma unroll
;         for (int ai = 0; ai < 2; ++ai)
; #pragma unroll
;             for (int m = 0; m < 4; ++m) { po.put(0, pack8(acc[ai][0][m][0] * qs, acc[ai][0][m][1] * qs)); po.put(1, pack8(acc[ai][1][m][0] * qs, acc[ai][1][m][1] * qs)); po.flush<true>(ai, m); }
;     }
.Lp1_epi_plain:
	v_cvt_pk_bf16_f32 v125, v124, v125
	v_cvt_pk_bf16_f32 v124, v122, v123
	v_cvt_pk_bf16_f32 v122, v126, v127
	v_cvt_pk_bf16_f32 v123, v128, v129
	ds_write_b128 v153, v[122:125]
	v_cvt_pk_bf16_f32 v113, v112, v113
	v_cvt_pk_bf16_f32 v112, v110, v111
	v_cvt_pk_bf16_f32 v110, v118, v119
	v_cvt_pk_bf16_f32 v111, v120, v121
	ds_write_b128 v153, v[110:113] offset:64
	ds_read_b128 v[110:113], v154
	ds_read_b128 v[118:121], v154 offset:1152
	v_lshl_add_u64 v[122:123], v[138:139], 0, s[24:25]
	s_waitcnt lgkmcnt(0)
	global_store_dwordx4 v[122:123], v[110:113], off nt
	global_store_dwordx4 v[122:123], v[118:121], off offset:1024 nt
	s_nop 0
	v_cvt_pk_bf16_f32 v109, v108, v109
	v_cvt_pk_bf16_f32 v108, v106, v107
	v_cvt_pk_bf16_f32 v106, v114, v115
	v_cvt_pk_bf16_f32 v107, v116, v117
	ds_write_b128 v153, v[106:109]
	v_cvt_pk_bf16_f32 v97, v96, v97
	v_cvt_pk_bf16_f32 v96, v94, v95
	v_cvt_pk_bf16_f32 v94, v102, v103
	v_cvt_pk_bf16_f32 v95, v104, v105
	ds_write_b128 v153, v[94:97] offset:64
	ds_read_b128 v[94:97], v154
	ds_read_b128 v[102:105], v154 offset:1152
	s_waitcnt lgkmcnt(0)
	global_store_dwordx4 v[122:123], v[94:97], off offset:2048 nt
	global_store_dwordx4 v[122:123], v[102:105], off offset:3072 nt
	s_nop 0
	v_cvt_pk_bf16_f32 v93, v92, v93
	v_cvt_pk_bf16_f32 v92, v90, v91
	v_cvt_pk_bf16_f32 v90, v98, v99
	v_cvt_pk_bf16_f32 v91, v100, v101
	ds_write_b128 v153, v[90:93]
	v_cvt_pk_bf16_f32 v85, v84, v85
	v_cvt_pk_bf16_f32 v84, v82, v83
	v_cvt_pk_bf16_f32 v82, v86, v87
	v_cvt_pk_bf16_f32 v83, v88, v89
	ds_write_b128 v153, v[82:85] offset:64
	ds_read_b128 v[82:85], v154
	ds_read_b128 v[86:89], v154 offset:1152
	v_add_co_u32_e32 v90, vcc, s58, v122
	s_nop 0
	s_nop 0
	v_addc_co_u32_e32 v91, vcc, 0, v123, vcc
	s_waitcnt lgkmcnt(0)
	global_store_dwordx4 v[90:91], v[82:85], off nt
	global_store_dwordx4 v[90:91], v[86:89], off offset:1024 nt
	v_cvt_pk_bf16_f32 v77, v76, v77
	v_cvt_pk_bf16_f32 v76, v74, v75
	v_cvt_pk_bf16_f32 v74, v78, v79
	v_cvt_pk_bf16_f32 v75, v80, v81
	ds_write_b128 v153, v[74:77]
	v_cvt_pk_bf16_f32 v69, v68, v69
	v_cvt_pk_bf16_f32 v68, v66, v67
	v_cvt_pk_bf16_f32 v66, v70, v71
	v_cvt_pk_bf16_f32 v67, v72, v73
	ds_write_b128 v153, v[66:69] offset:64
	ds_read_b128 v[66:69], v154
	ds_read_b128 v[70:73], v154 offset:1152
	s_waitcnt lgkmcnt(0)
	global_store_dwordx4 v[90:91], v[66:69], off offset:2048 nt
	global_store_dwordx4 v[90:91], v[70:73], off offset:3072 nt
	v_cvt_pk_bf16_f32 v61, v60, v61
	v_cvt_pk_bf16_f32 v60, v58, v59
	v_cvt_pk_bf16_f32 v58, v62, v63
	v_cvt_pk_bf16_f32 v59, v64, v65
	ds_write_b128 v153, v[58:61]
	v_cvt_pk_bf16_f32 v53, v52, v53
	v_cvt_pk_bf16_f32 v52, v50, v51
	v_cvt_pk_bf16_f32 v50, v54, v55
	v_cvt_pk_bf16_f32 v51, v56, v57
	ds_write_b128 v153, v[50:53] offset:64
	ds_read_b128 v[50:53], v154
	ds_read_b128 v[54:57], v154 offset:1152
	v_add_co_u32_e32 v58, vcc, s52, v122
	s_nop 0
	s_nop 0
	v_addc_co_u32_e32 v59, vcc, 0, v123, vcc
	v_add_co_u32_e32 v60, vcc, s59, v122
	s_nop 0
	s_nop 0
	v_addc_co_u32_e32 v61, vcc, 0, v123, vcc
	s_waitcnt lgkmcnt(0)
	global_store_dwordx4 v[60:61], v[50:53], off offset:-4096 nt
	global_store_dwordx4 v[58:59], v[54:57], off offset:1024 nt
	v_cvt_pk_bf16_f32 v45, v44, v45
	v_cvt_pk_bf16_f32 v44, v42, v43
	v_cvt_pk_bf16_f32 v42, v46, v47
	v_cvt_pk_bf16_f32 v43, v48, v49
	ds_write_b128 v153, v[42:45]
	v_cvt_pk_bf16_f32 v33, v32, v33
	v_cvt_pk_bf16_f32 v32, v30, v31
	v_cvt_pk_bf16_f32 v30, v38, v39
	v_cvt_pk_bf16_f32 v31, v40, v41
	ds_write_b128 v153, v[30:33] offset:64
	ds_read_b128 v[30:33], v154
	ds_read_b128 v[38:41], v154 offset:1152
	s_waitcnt lgkmcnt(0)
	global_store_dwordx4 v[58:59], v[30:33], off offset:2048 nt
	global_store_dwordx4 v[58:59], v[38:41], off offset:3072 nt
	s_nop 0
	v_cvt_pk_bf16_f32 v29, v28, v29
	v_cvt_pk_bf16_f32 v28, v26, v27
	v_cvt_pk_bf16_f32 v26, v34, v35
	v_cvt_pk_bf16_f32 v27, v36, v37
	ds_write_b128 v153, v[26:29]
	v_cvt_pk_bf16_f32 v17, v16, v17
	v_cvt_pk_bf16_f32 v16, v14, v15
	v_cvt_pk_bf16_f32 v14, v22, v23
	v_cvt_pk_bf16_f32 v15, v24, v25
	ds_write_b128 v153, v[14:17] offset:64
	ds_read_b128 v[14:17], v154
	ds_read_b128 v[22:25], v154 offset:1152
	s_waitcnt lgkmcnt(0)
	global_store_dwordx4 v[60:61], v[14:17], off nt
	global_store_dwordx4 v[60:61], v[22:25], off offset:1024 nt
	s_nop 0
	v_cvt_pk_bf16_f32 v13, v12, v13
	v_cvt_pk_bf16_f32 v12, v10, v11
	v_cvt_pk_bf16_f32 v10, v18, v19
	v_cvt_pk_bf16_f32 v11, v20, v21
	ds_write_b128 v153, v[10:13]
	v_cvt_pk_bf16_f32 v5, v4, v5
	v_cvt_pk_bf16_f32 v4, v2, v3
	v_cvt_pk_bf16_f32 v2, v6, v7
	v_cvt_pk_bf16_f32 v3, v8, v9
	ds_write_b128 v153, v[2:5] offset:64
	ds_read_b128 v[2:5], v154
	ds_read_b128 v[6:9], v154 offset:1152
	s_andn2_b64 vcc, exec, s[4:5]
	s_mov_b64 s[4:5], -1
	s_waitcnt lgkmcnt(0)
	global_store_dwordx4 v[60:61], v[2:5], off offset:2048 nt
	global_store_dwordx4 v[60:61], v[6:9], off offset:3072 nt
	s_branch .Lp1_epi_join
